# MLA key loop: waves 4-7 delayed by s_sleep 8 after each stage barrier (stagger softmax against partner MFMA)
# speedup vs baseline: 1.0086x; 1.0076x over previous
; template <int DQK, int MODE, bool QN, bool KN> ...
;     ...
;   f32x4 gk0 = {1.f, 1.f, 1.f, 1.f}, gk1 = {1.f, 1.f, 1.f, 1.f};
;   if (KN) { gk0 = *(const f32x4*)(gk + (tid & 7) * 8); gk1 = *(const f32x4*)(gk + (tid & 7) * 8 + 4); }
;   float sbound = 0.f; bool fixed_shift = false;
;   if (MODE != 2 && QN) {
;     float gqm = 0.f, gkm = 0.f;
; #pragma unroll
;     for (int s = 0; s < NS; ++s)
; #pragma unroll
;       for (int j = 0; j < 8; ++j) { gqm = fmaxf(gqm, fabsf(gq[16 * s + 8 * h + j])); gkm = fmaxf(gkm, fabsf(gk[16 * s + 8 * h + j])); }
;     gqm = fmaxf(gqm, __shfl_xor(gqm, 32)); gkm = fmaxf(gkm, __shfl_xor(gkm, 32));
;     sbound = sqrtf((float)DQK) * 1.4426950408889634f * gqm * gkm * 1.02f + 0.01f;
;     fixed_shift = __builtin_amdgcn_readfirstlane(sbound < 48.f ? 1 : 0) != 0;
;   }
;   f32x16 o[2];
; #pragma unroll
;   for (int a = 0; a < 2; ++a)
; #pragma unroll
;     for (int i = 0; i < 16; ++i) o[a][i] = 0.f;
;   float m_run = -INFINITY, l_run = 0.f, carry = 1.f;
; template <int LAYER>
; DI void attn_phase(const Params& p, char* smem) {
;   char* ws = p.ws;
;   bf16_t* mix = (bf16_t*)(ws + O_MIX);
;   const int xcd = (int)(blockIdx.x & 7), lb = (int)(blockIdx.x >> 3), L = (int)(gridDim.x >> 3);
;   for (int j = lb; j < 192 + 64; j += L) {
;     if (j < 192) {
;       const int hl = j >> 4, qi = j & 15, qt = ((j / L) & 1) ? (15 - qi) : qi, bh = hl * 8 + xcd, b = bh / 12, hd = bh % 12, q0 = qt * 256;
;       const size_t tok0 = (size_t)b * SEQ;
;       bf16_t* O = mix + (tok0 + q0) * DM + hd * 64;
;       if (LAYER == 0) {
;         const bf16_t* P = (const bf16_t*)(ws + O_P);
;         attn_item<64, 2, false, false>(P + (tok0 + q0) * 2560 + hd * 64, 2560, P + tok0 * 2560 + 768 + hd * 64, 2560, P + tok0 * 2560 + 1536 + hd * 64, 2560,
;                                        q0, q0 / 64 + 4, O, 0.125f, smem, nullptr, 1.f, nullptr, nullptr);
;       } else {
;         const bf16_t* Qb = (const bf16_t*)(ws + O_QB);
;         const bf16_t* Kn = (const bf16_t*)(ws + O_KN);
;         const bf16_t* V1 = (const bf16_t*)(ws + O_V1);
;         attn_item<96, 1, true, false>(Qb + (tok0 + q0) * 1152 + hd * 96, 1152, Kn + tok0 * 1152 + hd * 96, 1152, V1 + tok0 * 768 + hd * 64, 768,
;                                       q0, q0 / 64 + 4, O, 1.f, smem, p.mla_g_qn, 0.14724138410008716f, p.pos + tok0 + q0, p.mla_g_kn);
.LBB0_1164:
	s_or_b64 exec, exec, s[0:1]
	v_readlane_b32 s0, v254, 25
	v_readlane_b32 s1, v254, 26
	s_andn2_b64 vcc, exec, s[0:1]
	s_waitcnt lgkmcnt(0)
	s_barrier
	s_cbranch_vccnz .LBB0_1237
	s_lshl_b32 s9, s52, 12
	s_lshl_b32 s0, s52, 18
	s_add_u32 s0, s86, s0
	s_addc_u32 s1, s87, 0
	v_mbcnt_hi_u32_b32 v226, -1, v213
	s_add_u32 s24, s0, 0xb7a0000
	s_mov_b32 s0, 0x11000
	v_and_b32_e32 v0, 64, v226
	s_mov_b32 s7, 0
	s_addc_u32 s25, s1, 0
	s_movk_i32 s26, 0xb00
	s_movk_i32 s27, 0xffe0
	v_mov_b32_e32 v1, 0
	s_mov_b32 s8, 0x3c800000
	s_mov_b32 s28, 0x800000
	v_mov_b32_e32 v215, 0x3c23d70a
	s_mov_b32 s29, 0x42400000
	s_mov_b32 s30, 0x20000
	s_movk_i32 s31, 0x90
	s_movk_i32 s34, 0x110
	s_mov_b32 s35, 0xff800000
	s_movk_i32 s36, 0x900
	s_movk_i32 s37, 0x600
	s_mov_b32 s38, 0xc2fc0000
	v_mov_b32_e32 v214, 0x358637bd
	s_mov_b32 s39, 0x2aaaaaab
	s_movk_i32 s40, 0xd0
	s_add_i32 s41, s0, 0x110
	v_xor_b32_e32 v227, 32, v226
	v_add_u32_e32 v228, 64, v0
	v_xor_b32_e32 v229, 1, v226
	v_xor_b32_e32 v230, 2, v226
	v_xor_b32_e32 v231, 4, v226
	v_mov_b32_e32 v232, 0x42800000
	v_not_b32_e32 v233, 63
	v_mov_b32_e32 v234, 0xff800000
	v_readfirstlane_b32 s101, v212
	s_nop 3
	s_lshr_b32 s101, s101, 8
	s_branch .LBB0_1168

; #define AT_SB __builtin_amdgcn_sched_barrier(0);
; template <int DQK, int MODE, bool QN, bool KN> ...
;     ...
;   for (int sg = 0; sg < nsg; sg += 2) {
;     AT_SB AT_GLOAD(rk0, rv0, sg + 2)
;     AT_SB compute(2 * sg, 0); compute(2 * sg + 1, 0); AT_SB
.LBB0_1198:
	s_cmp_lg_u32 s101, 0
	s_cbranch_scc0 .Lstg_a
	s_sleep 8

; #define MFMA32(a, b, c) __builtin_amdgcn_mfma_f32_32x32x16_bf16((a), (b), (c), 0, 0, 0)
; #define AT_SB __builtin_amdgcn_sched_barrier(0);
; template <int DQK, int MODE, bool QN, bool KN> ...
;     ...
;         for (int s = 0; s < NS; ++s) {
;           const bf16x8 kf = *(const bf16x8*)(sK + (kb * 32 + r) * KROW + s * 32 + h * 16);
;           sacc[kb] = MFMA32(kf, qf[s], sacc[kb]);
;         }
;       }
;       const bool diag = (MODE != 0) && (kt * 64 + 63 >= q0 + wave * 32);
;       if (MODE != 0 && diag) {
; #pragma unroll
;         for (int kb = 0; kb < 2; ++kb)
; #pragma unroll
;           for (int i = 0; i < 16; ++i) {
;             const int key = kt * 64 + kb * 32 + (i & 3) + 8 * (i >> 2) + 4 * h;
;             if (MODE == 1 ? (key > qrow) : (key >= qrow)) sacc[kb][i] = -INFINITY;
;           }
;       }
;     ...
;     AT_SWRITE(rk1, rv1, 1)
;     if (MODE == 2) { if (__syncthreads_and(carry < 1.17549435e-38f)) break; } else { __syncthreads(); }
;     AT_SB AT_GLOAD(rk1, rv1, sg + 3)
;     AT_SB compute(2 * sg + 2, 1); compute(2 * sg + 3, 1); AT_SB
.LBB0_1218:
	s_or_b64 exec, exec, s[2:3]
	s_waitcnt vmcnt(9)
	ds_write_b128 v244, v[184:187] offset:43008
	s_waitcnt vmcnt(8)
	ds_write_b128 v245, v[188:191] offset:43008
	s_waitcnt vmcnt(7)
	ds_write_b128 v246, v[192:195] offset:43008
	s_waitcnt vmcnt(6)
	ds_write_b128 v250, v[196:199]
	s_waitcnt vmcnt(5)
	ds_write_b128 v250, v[200:203] offset:4096
	s_waitcnt lgkmcnt(0)
	s_barrier
	s_cmp_lg_u32 s101, 0
	s_cbranch_scc0 .Lstg_b
	s_sleep 8
.Lstg_b:
	s_min_i32 s2, s45, s13
	s_lshl_b32 s4, s2, 7
	v_add_u32_e32 v0, s4, v238
	v_mad_i64_i32 v[14:15], s[2:3], v0, s36, v[220:221]
	v_add_u32_e32 v0, s4, v239
	v_mad_i64_i32 v[64:65], s[2:3], v0, s36, v[222:223]
	v_add_u32_e32 v0, s4, v240
	global_load_dwordx4 v[184:187], v[14:15], off
	global_load_dwordx4 v[188:191], v[64:65], off
	v_mad_i64_i32 v[14:15], s[2:3], v0, s36, v[224:225]
	v_add_u32_e32 v0, s4, v241
	v_mad_i64_i32 v[64:65], s[2:3], v0, s37, v[218:219]
	v_add_u32_e32 v0, s4, v242
	global_load_dwordx4 v[192:195], v[14:15], off
	global_load_dwordx4 v[196:199], v[64:65], off
	v_mad_i64_i32 v[14:15], s[2:3], v0, s37, v[218:219]
	global_load_dwordx4 v[200:203], v[14:15], off
	s_add_i32 s2, s53, 0xffffff81
	v_cmp_le_i32_e32 vcc, s2, v243
	s_and_saveexec_b64 s[2:3], vcc
	s_cbranch_execz .LBB0_1228
	ds_read_b128 v[32:35], v251 offset:43008
	ds_read_b128 v[36:39], v251 offset:43040
	ds_read_b128 v[40:43], v251 offset:43072
	ds_read_b128 v[44:47], v251 offset:43104
	ds_read_b128 v[48:51], v251 offset:43136
	ds_read_b128 v[52:55], v251 offset:43168
	ds_read_b128 v[112:115], v251 offset:49664
	ds_read_b128 v[116:119], v251 offset:49696
	ds_read_b128 v[120:123], v251 offset:49728
	ds_read_b128 v[124:127], v251 offset:49760
	ds_read_b128 v[144:147], v251 offset:49792
	ds_read_b128 v[148:151], v251 offset:49824
	s_sub_i32 s4, s53, 64
	v_cmp_ge_i32_e32 vcc, s4, v236
	s_waitcnt lgkmcnt(11)
	v_mfma_f32_32x32x16_bf16 v[80:95], v[32:35], v[160:163], v[16:31]
	s_waitcnt lgkmcnt(10)
	v_mfma_f32_32x32x16_bf16 v[80:95], v[36:39], v[164:167], v[80:95]
	s_waitcnt lgkmcnt(9)
	v_mfma_f32_32x32x16_bf16 v[80:95], v[40:43], v[168:171], v[80:95]
	s_waitcnt lgkmcnt(8)
	v_mfma_f32_32x32x16_bf16 v[80:95], v[44:47], v[172:175], v[80:95]
	s_waitcnt lgkmcnt(7)
	v_mfma_f32_32x32x16_bf16 v[80:95], v[48:51], v[176:179], v[80:95]
	s_waitcnt lgkmcnt(6)
	v_mfma_f32_32x32x16_bf16 v[80:95], v[52:55], v[180:183], v[80:95]
	s_waitcnt lgkmcnt(5)
	v_mfma_f32_32x32x16_bf16 v[64:79], v[112:115], v[160:163], v[16:31]
	s_waitcnt lgkmcnt(4)
	v_mfma_f32_32x32x16_bf16 v[64:79], v[116:119], v[164:167], v[64:79]
	s_waitcnt lgkmcnt(3)
	v_mfma_f32_32x32x16_bf16 v[64:79], v[120:123], v[168:171], v[64:79]
	s_waitcnt lgkmcnt(2)
	v_mfma_f32_32x32x16_bf16 v[64:79], v[124:127], v[172:175], v[64:79]
	s_waitcnt lgkmcnt(1)
	v_mfma_f32_32x32x16_bf16 v[64:79], v[144:147], v[176:179], v[64:79]
	s_waitcnt lgkmcnt(0)
	v_mfma_f32_32x32x16_bf16 v[64:79], v[148:151], v[180:183], v[64:79]
	s_and_saveexec_b64 s[10:11], vcc
	s_cbranch_execz .LBB0_1221
	v_add_u32_e32 v0, s53, v247
	v_add_u32_e32 v14, 0xffffff81, v0
	v_cmp_le_i32_e32 vcc, v14, v237
	v_add_u32_e32 v14, 0xffffff82, v0
	s_nop 0
	v_cndmask_b32_e32 v80, v234, v80, vcc
	v_cmp_le_i32_e32 vcc, v14, v237
	v_add_u32_e32 v14, 0xffffff83, v0
	s_nop 0
	v_cndmask_b32_e32 v81, v234, v81, vcc
	v_cmp_le_i32_e32 vcc, v14, v237
	v_add_u32_e32 v14, 0xffffff84, v0
	s_nop 0
	v_cndmask_b32_e32 v82, v234, v82, vcc
	v_cmp_le_i32_e32 vcc, v14, v237
	v_add_u32_e32 v14, 0xffffff89, v0
	s_nop 0
	v_cndmask_b32_e32 v83, v234, v83, vcc
	v_cmp_le_i32_e32 vcc, v14, v237
	v_add_u32_e32 v14, 0xffffff8a, v0
	s_nop 0
	v_cndmask_b32_e32 v84, v234, v84, vcc
	v_cmp_le_i32_e32 vcc, v14, v237
	v_add_u32_e32 v14, 0xffffff8b, v0
	s_nop 0
	v_cndmask_b32_e32 v85, v234, v85, vcc
	v_cmp_le_i32_e32 vcc, v14, v237
	v_add_u32_e32 v14, 0xffffff8c, v0
	s_nop 0
	v_cndmask_b32_e32 v86, v234, v86, vcc
	v_cmp_le_i32_e32 vcc, v14, v237
	v_add_u32_e32 v14, 0xffffff91, v0
	s_nop 0
	v_cndmask_b32_e32 v87, v234, v87, vcc
	v_cmp_le_i32_e32 vcc, v14, v237
	v_add_u32_e32 v14, 0xffffff92, v0
	s_nop 0
	v_cndmask_b32_e32 v88, v234, v88, vcc
	v_cmp_le_i32_e32 vcc, v14, v237
	v_add_u32_e32 v14, 0xffffff93, v0
	s_nop 0
	v_cndmask_b32_e32 v89, v234, v89, vcc
	v_cmp_le_i32_e32 vcc, v14, v237
	v_add_u32_e32 v14, 0xffffff94, v0
	s_nop 0
	v_cndmask_b32_e32 v90, v234, v90, vcc
	v_cmp_le_i32_e32 vcc, v14, v237
	v_add_u32_e32 v14, 0xffffff99, v0
	s_nop 0
	v_cndmask_b32_e32 v91, v234, v91, vcc
	v_cmp_le_i32_e32 vcc, v14, v237
	v_add_u32_e32 v14, 0xffffff9a, v0
	s_nop 0
	v_cndmask_b32_e32 v92, v234, v92, vcc
	v_cmp_le_i32_e32 vcc, v14, v237
	v_add_u32_e32 v14, 0xffffff9b, v0
	s_nop 0
	v_cndmask_b32_e32 v93, v234, v93, vcc
	v_cmp_le_i32_e32 vcc, v14, v237
	v_add_u32_e32 v14, 0xffffff9c, v0
	s_nop 0
	v_cndmask_b32_e32 v94, v234, v94, vcc
	v_cmp_le_i32_e32 vcc, v14, v237
	v_add_u32_e32 v14, 0xffffffa1, v0
	s_nop 0
	v_cndmask_b32_e32 v95, v234, v95, vcc
	v_cmp_le_i32_e32 vcc, v14, v237
	v_add_u32_e32 v14, 0xffffffa2, v0
	s_nop 0
	v_cndmask_b32_e32 v64, v234, v64, vcc
	v_cmp_le_i32_e32 vcc, v14, v237
	v_add_u32_e32 v14, 0xffffffa3, v0
	s_nop 0
	v_cndmask_b32_e32 v65, v234, v65, vcc
	v_cmp_le_i32_e32 vcc, v14, v237
	v_add_u32_e32 v14, 0xffffffa4, v0
	s_nop 0
	v_cndmask_b32_e32 v66, v234, v66, vcc
	v_cmp_le_i32_e32 vcc, v14, v237
	v_add_u32_e32 v14, 0xffffffa9, v0
	s_nop 0
	v_cndmask_b32_e32 v67, v234, v67, vcc
	v_cmp_le_i32_e32 vcc, v14, v237
	v_add_u32_e32 v14, 0xffffffaa, v0
	s_nop 0
	v_cndmask_b32_e32 v68, v234, v68, vcc
	v_cmp_le_i32_e32 vcc, v14, v237
	v_add_u32_e32 v14, 0xffffffab, v0
	s_nop 0
	v_cndmask_b32_e32 v69, v234, v69, vcc
	v_cmp_le_i32_e32 vcc, v14, v237
	v_add_u32_e32 v14, 0xffffffac, v0
	s_nop 0
	v_cndmask_b32_e32 v70, v234, v70, vcc
	v_cmp_le_i32_e32 vcc, v14, v237
	v_add_u32_e32 v14, 0xffffffb1, v0
	s_nop 0
	v_cndmask_b32_e32 v71, v234, v71, vcc
	v_cmp_le_i32_e32 vcc, v14, v237
	v_add_u32_e32 v14, 0xffffffb2, v0
	s_nop 0
	v_cndmask_b32_e32 v72, v234, v72, vcc
	v_cmp_le_i32_e32 vcc, v14, v237
	v_add_u32_e32 v14, 0xffffffb3, v0
	s_nop 0
	v_cndmask_b32_e32 v73, v234, v73, vcc
	v_cmp_le_i32_e32 vcc, v14, v237
	v_add_u32_e32 v14, 0xffffffb4, v0
	s_nop 0
	v_cndmask_b32_e32 v74, v234, v74, vcc
	v_cmp_le_i32_e32 vcc, v14, v237
	v_add_u32_e32 v14, 0xffffffb9, v0
	s_nop 0
	v_cndmask_b32_e32 v75, v234, v75, vcc
	v_cmp_le_i32_e32 vcc, v14, v237
	v_add_u32_e32 v14, 0xffffffba, v0
	s_nop 0
	v_cndmask_b32_e32 v76, v234, v76, vcc
	v_cmp_le_i32_e32 vcc, v14, v237
	v_add_u32_e32 v14, 0xffffffbb, v0
	v_add_u32_e32 v0, 0xffffffbc, v0
	v_cndmask_b32_e32 v77, v234, v77, vcc
	v_cmp_le_i32_e32 vcc, v14, v237
	s_nop 1
	v_cndmask_b32_e32 v78, v234, v78, vcc
	v_cmp_le_i32_e32 vcc, v0, v237
	s_nop 1
	v_cndmask_b32_e32 v79, v234, v79, vcc
